# second static mixers item indexed by workgroup id again (decoupled from the XCD-local attention remap)
# speedup vs baseline: 1.0023x; 1.0023x over previous
.LBB0_577:
	v_sub_f32_e32 v1, v37, v0
	v_exp_f32_e32 v1, v1
	v_sub_f32_e32 v3, v45, v0
	v_exp_f32_e32 v3, v3
	s_waitcnt vmcnt(12)
	v_sub_f32_e32 v4, v47, v0
	v_exp_f32_e32 v4, v4
	v_sub_f32_e32 v5, v46, v0
	v_exp_f32_e32 v5, v5
	v_sub_f32_e32 v6, v8, v0
	v_add_f32_e32 v2, v1, v39
	v_exp_f32_e32 v6, v6
	v_sub_f32_e32 v7, v9, v0
	v_add_f32_e32 v2, v3, v2
	v_exp_f32_e32 v7, v7
	v_sub_f32_e32 v8, v10, v0
	v_add_f32_e32 v2, v4, v2
	v_exp_f32_e32 v8, v8
	v_sub_f32_e32 v9, v11, v0
	v_add_f32_e32 v2, v5, v2
	v_exp_f32_e32 v9, v9
	v_sub_f32_e32 v10, v12, v0
	v_add_f32_e32 v2, v6, v2
	v_exp_f32_e32 v10, v10
	v_sub_f32_e32 v11, v13, v0
	v_add_f32_e32 v2, v7, v2
	v_exp_f32_e32 v11, v11
	v_sub_f32_e32 v12, v14, v0
	v_add_f32_e32 v2, v8, v2
	v_exp_f32_e32 v36, v12
	v_sub_f32_e32 v12, v15, v0
	v_add_f32_e32 v2, v9, v2
	v_exp_f32_e32 v15, v12
	v_sub_f32_e32 v12, v16, v0
	v_add_f32_e32 v2, v10, v2
	v_exp_f32_e32 v37, v12
	v_sub_f32_e32 v12, v17, v0
	v_add_f32_e32 v2, v11, v2
	v_exp_f32_e32 v38, v12
	v_sub_f32_e32 v12, v18, v0
	v_add_f32_e32 v2, v36, v2
	v_exp_f32_e32 v39, v12
	v_sub_f32_e32 v12, v19, v0
	v_add_f32_e32 v2, v15, v2
	v_exp_f32_e32 v45, v12
	v_sub_f32_e32 v12, v20, v0
	v_add_f32_e32 v2, v37, v2
	v_exp_f32_e32 v20, v12
	v_sub_f32_e32 v12, v21, v0
	v_add_f32_e32 v2, v38, v2
	v_exp_f32_e32 v21, v12
	v_sub_f32_e32 v12, v22, v0
	v_add_f32_e32 v2, v39, v2
	v_exp_f32_e32 v22, v12
	v_sub_f32_e32 v12, v23, v0
	v_add_f32_e32 v2, v45, v2
	v_exp_f32_e32 v23, v12
	v_sub_f32_e32 v12, v24, v0
	v_add_f32_e32 v2, v20, v2
	v_exp_f32_e32 v24, v12
	v_sub_f32_e32 v12, v25, v0
	v_add_f32_e32 v2, v21, v2
	v_exp_f32_e32 v25, v12
	v_sub_f32_e32 v12, v26, v0
	v_add_f32_e32 v2, v22, v2
	v_exp_f32_e32 v26, v12
	v_sub_f32_e32 v12, v27, v0
	v_add_f32_e32 v2, v23, v2
	v_exp_f32_e32 v27, v12
	v_sub_f32_e32 v12, v28, v0
	v_add_f32_e32 v2, v24, v2
	v_exp_f32_e32 v28, v12
	v_sub_f32_e32 v12, v29, v0
	v_add_f32_e32 v2, v25, v2
	v_exp_f32_e32 v29, v12
	v_sub_f32_e32 v12, v30, v0
	v_add_f32_e32 v2, v26, v2
	v_exp_f32_e32 v30, v12
	v_sub_f32_e32 v12, v31, v0
	v_add_f32_e32 v2, v27, v2
	v_exp_f32_e32 v31, v12
	v_sub_f32_e32 v12, v32, v0
	v_add_f32_e32 v2, v28, v2
	v_exp_f32_e32 v32, v12
	v_sub_f32_e32 v12, v33, v0
	v_add_f32_e32 v2, v29, v2
	v_exp_f32_e32 v33, v12
	v_sub_f32_e32 v12, v34, v0
	v_add_f32_e32 v2, v30, v2
	v_exp_f32_e32 v34, v12
	v_sub_f32_e32 v12, v35, v0
	v_add_f32_e32 v2, v31, v2
	v_exp_f32_e32 v35, v12
	v_sub_f32_e32 v12, v41, v0
	v_add_f32_e32 v2, v32, v2
	v_exp_f32_e32 v41, v12
	v_sub_f32_e32 v12, v40, v0
	v_add_f32_e32 v2, v33, v2
	v_exp_f32_e32 v40, v12
	v_sub_f32_e32 v12, v43, v0
	v_add_f32_e32 v2, v34, v2
	v_exp_f32_e32 v43, v12
	v_sub_f32_e32 v12, v42, v0
	v_add_f32_e32 v2, v35, v2
	v_exp_f32_e32 v42, v12
	v_add_f32_e32 v2, v41, v2
	v_add_f32_e32 v2, v40, v2
	v_add_f32_e32 v2, v43, v2
	v_add_f32_e32 v2, v42, v2
	ds_bpermute_b32 v12, v69, v2
	v_sub_f32_e32 v0, v67, v0
	v_exp_f32_e32 v0, v0
	v_cvt_pk_bf16_f32 v16, v44, v44
	v_cvt_pk_bf16_f32 v17, v44, v44
	s_waitcnt lgkmcnt(0)
	v_add_f32_e32 v2, v2, v12
	ds_bpermute_b32 v12, v71, v2
	v_cvt_pk_bf16_f32 v18, v1, v3
	v_cvt_pk_bf16_f32 v19, v4, v5
	v_mov_b32_e32 v61, v63
	s_waitcnt lgkmcnt(0)
	v_add_f32_e32 v2, v2, v12
	v_add_f32_e32 v46, v0, v2
	v_cvt_pk_bf16_f32 v12, v6, v7
	v_cvt_pk_bf16_f32 v13, v8, v9
	v_cvt_pk_bf16_f32 v14, v10, v11
	v_cvt_pk_bf16_f32 v15, v36, v15
	v_cvt_pk_bf16_f32 v8, v37, v38
	v_cvt_pk_bf16_f32 v9, v39, v45
	v_cvt_pk_bf16_f32 v10, v20, v21
	v_div_scale_f32 v20, s[10:11], v46, v46, 1.0
	v_rcp_f32_e32 v21, v20
	v_cvt_pk_bf16_f32 v11, v22, v23
	v_cvt_pk_bf16_f32 v4, v24, v25
	v_cvt_pk_bf16_f32 v5, v26, v27
	v_cvt_pk_bf16_f32 v6, v28, v29
	v_cvt_pk_bf16_f32 v7, v30, v31
	s_nop 0
	v_fma_f32 v22, -v20, v21, 1.0
	v_fmac_f32_e32 v21, v22, v21
	v_div_scale_f32 v22, vcc, 1.0, v46, 1.0
	v_mul_f32_e32 v23, v22, v21
	v_fma_f32 v24, -v20, v23, v22
	v_cvt_pk_bf16_f32 v0, v32, v33
	v_cvt_pk_bf16_f32 v1, v34, v35
	v_cvt_pk_bf16_f32 v2, v41, v40
	v_cvt_pk_bf16_f32 v3, v43, v42
	v_fmac_f32_e32 v23, v24, v21
	ds_read2_b64 v[24:27], v55 offset0:8 offset1:12
	ds_read2_b64 v[28:31], v55 offset0:16 offset1:20
	s_waitcnt lgkmcnt(1)
	v_mfma_f32_16x16x32_bf16 v[24:27], v[24:27], v[16:19], 0
	v_fma_f32 v20, -v20, v23, v22
	v_div_fmas_f32 v20, v20, v21, v23
	v_div_fixup_f32 v22, v20, v46, 1.0
	s_waitcnt lgkmcnt(0)
	v_mfma_f32_16x16x32_bf16 v[24:27], v[28:31], v[12:15], v[24:27]
	ds_read2_b64 v[28:31], v55 offset0:24 offset1:28
	v_lshlrev_b64 v[20:21], 11, v[60:61]
	v_lshl_add_u64 v[20:21], v[52:53], 0, v[20:21]
	s_waitcnt lgkmcnt(0)
	v_mfma_f32_16x16x32_bf16 v[24:27], v[28:31], v[8:11], v[24:27]
	ds_read2_b64 v[28:31], v55 offset0:32 offset1:36
	s_waitcnt lgkmcnt(0)
	v_mfma_f32_16x16x32_bf16 v[24:27], v[28:31], v[4:7], v[24:27]
	ds_read2_b64 v[28:31], v55 offset0:40 offset1:44
	s_waitcnt lgkmcnt(0)
	v_mfma_f32_16x16x32_bf16 v[24:27], v[28:31], v[0:3], v[24:27]
	s_nop 7
	v_pk_mul_f32 v[24:25], v[24:25], v[22:23] op_sel_hi:[1,0]
	v_pk_mul_f32 v[26:27], v[26:27], v[22:23] op_sel_hi:[1,0]
	v_cvt_pk_bf16_f32 v24, v24, v25
	s_nop 0
	v_cvt_pk_bf16_f32 v25, v26, v27
	global_store_dwordx2 v[20:21], v[24:25], off
	ds_read2_b64 v[24:27], v56 offset0:40 offset1:44
	ds_read2_b64 v[28:31], v56 offset0:48 offset1:52
	s_waitcnt lgkmcnt(1)
	v_mfma_f32_16x16x32_bf16 v[24:27], v[24:27], v[16:19], 0
	s_waitcnt lgkmcnt(0)
	v_mfma_f32_16x16x32_bf16 v[24:27], v[28:31], v[12:15], v[24:27]
	ds_read2_b64 v[28:31], v56 offset0:56 offset1:60
	s_waitcnt lgkmcnt(0)
	v_mfma_f32_16x16x32_bf16 v[24:27], v[28:31], v[8:11], v[24:27]
	ds_read2_b64 v[28:31], v56 offset0:64 offset1:68
	s_waitcnt lgkmcnt(0)
	v_mfma_f32_16x16x32_bf16 v[24:27], v[28:31], v[4:7], v[24:27]
	ds_read2_b64 v[28:31], v56 offset0:72 offset1:76
	s_waitcnt lgkmcnt(0)
	v_mfma_f32_16x16x32_bf16 v[24:27], v[28:31], v[0:3], v[24:27]
	s_nop 7
	v_pk_mul_f32 v[24:25], v[22:23], v[24:25] op_sel_hi:[0,1]
	v_pk_mul_f32 v[26:27], v[22:23], v[26:27] op_sel_hi:[0,1]
	v_cvt_pk_bf16_f32 v24, v24, v25
	v_cvt_pk_bf16_f32 v25, v26, v27
	global_store_dwordx2 v[20:21], v[24:25], off offset:32
	ds_read2_b64 v[24:27], v57 offset0:72 offset1:76
	ds_read2_b64 v[28:31], v57 offset0:80 offset1:84
	s_waitcnt lgkmcnt(1)
	v_mfma_f32_16x16x32_bf16 v[24:27], v[24:27], v[16:19], 0
	s_waitcnt lgkmcnt(0)
	v_mfma_f32_16x16x32_bf16 v[24:27], v[28:31], v[12:15], v[24:27]
	ds_read2_b64 v[28:31], v57 offset0:88 offset1:92
	s_waitcnt lgkmcnt(0)
	v_mfma_f32_16x16x32_bf16 v[24:27], v[28:31], v[8:11], v[24:27]
	ds_read2_b64 v[28:31], v57 offset0:96 offset1:100
	s_waitcnt lgkmcnt(0)
	v_mfma_f32_16x16x32_bf16 v[24:27], v[28:31], v[4:7], v[24:27]
	ds_read2_b64 v[28:31], v57 offset0:104 offset1:108
	s_waitcnt lgkmcnt(0)
	v_mfma_f32_16x16x32_bf16 v[24:27], v[28:31], v[0:3], v[24:27]
	s_nop 7
	v_pk_mul_f32 v[24:25], v[22:23], v[24:25] op_sel_hi:[0,1]
	v_pk_mul_f32 v[26:27], v[22:23], v[26:27] op_sel_hi:[0,1]
	v_cvt_pk_bf16_f32 v24, v24, v25
	v_cvt_pk_bf16_f32 v25, v26, v27
	global_store_dwordx2 v[20:21], v[24:25], off offset:64
	ds_read2_b64 v[24:27], v58 offset0:104 offset1:108
	s_waitcnt lgkmcnt(0)
	v_mfma_f32_16x16x32_bf16 v[16:19], v[24:27], v[16:19], 0
	ds_read2_b64 v[24:27], v58 offset0:112 offset1:116
	s_waitcnt lgkmcnt(0)
	v_mfma_f32_16x16x32_bf16 v[12:15], v[24:27], v[12:15], v[16:19]
	s_nop 4
	ds_read2_b64 v[16:19], v58 offset0:120 offset1:124
	s_waitcnt lgkmcnt(0)
	v_mfma_f32_16x16x32_bf16 v[8:11], v[16:19], v[8:11], v[12:15]
	s_nop 2
	ds_read2_b64 v[12:15], v58 offset0:128 offset1:132
	s_waitcnt lgkmcnt(0)
	v_mfma_f32_16x16x32_bf16 v[4:7], v[12:15], v[4:7], v[8:11]
	s_nop 2
	ds_read2_b64 v[8:11], v58 offset0:136 offset1:140
	s_waitcnt lgkmcnt(0)
	v_mfma_f32_16x16x32_bf16 v[0:3], v[8:11], v[0:3], v[4:7]
	s_nop 7
	v_pk_mul_f32 v[0:1], v[22:23], v[0:1] op_sel_hi:[0,1]
	v_pk_mul_f32 v[2:3], v[22:23], v[2:3] op_sel_hi:[0,1]
	v_cvt_pk_bf16_f32 v0, v0, v1
	v_cvt_pk_bf16_f32 v1, v2, v3
	global_store_dwordx2 v[20:21], v[0:1], off offset:96
	s_barrier
	s_add_i32 s81, s2, 0x100
	s_branch .Lq_remap
